# SGU item: bias pointer fetched with the item-start scalar loads; the two scalar loads after the W-build barrier removed
# baseline (speedup 1.0000x reference)
.LBB0_246:
	s_ashr_i32 s3, s2, 31
	s_cmpk_gt_i32 s2, 0x1ff
	s_mov_b64 s[6:7], -1
	s_cbranch_scc0 .LBB0_252
	s_lshl_b32 s6, s2, 3
	s_and_b32 s6, s6, 56
	s_bfe_u32 s7, s2, 0x30005
	s_or_b32 s6, s6, s7
	s_add_i32 s8, s2, 0xfffffe00
	s_lshl_b32 s6, s6, 2
	s_and_b32 s7, s8, 0xffffff00
	s_or_b32 s6, s6, s7
	s_bfe_u32 s7, s2, 0x20003
	s_or_b32 s9, s6, s7
	s_cmpk_lt_u32 s2, 0x400
	v_readlane_b32 s10, v253, 8
	s_cselect_b64 s[6:7], -1, 0
	v_readlane_b32 s11, v253, 9
	s_and_b64 s[6:7], s[10:11], s[6:7]
	s_and_b64 s[6:7], s[6:7], exec
	s_cselect_b32 s10, s9, s8
	s_waitcnt vmcnt(0)
	v_mov_b32_e32 v68, v208
	s_lshl_b32 s6, s10, 5
	s_load_dwordx2 s[8:9], s[0:1], 0xa8
	s_load_dwordx2 s[98:99], s[0:1], 0xa0
	s_load_dwordx2 s[100:101], s[0:1], 0xb0
	s_and_b32 s14, s10, 3
	s_and_b32 s11, s6, 0x7f80
	v_readlane_b32 s6, v255, 36
	s_or_b32 s6, s14, s6
	s_ashr_i32 s7, s6, 31
	s_lshl_b64 s[12:13], s[6:7], 16
	v_lshlrev_b32_e32 v0, 3, v68
	s_waitcnt lgkmcnt(0)
	s_add_u32 s8, s8, s12
	v_and_b32_e32 v73, 0x78, v0
	v_ashrrev_i32_e32 v74, 4, v68
	s_addc_u32 s9, s9, s13
	v_lshlrev_b32_e32 v0, 2, v73
	v_lshlrev_b32_e32 v4, 7, v74
	v_lshl_add_u64 v[2:3], s[8:9], 0, v[0:1]
	v_ashrrev_i32_e32 v5, 31, v4
	v_lshl_add_u64 v[4:5], v[4:5], 2, v[2:3]
	global_load_dwordx4 v[18:21], v[4:5], off offset:16
	global_load_dwordx4 v[22:25], v[4:5], off
	v_add_u32_e32 v4, s11, v74
	v_ashrrev_i32_e32 v5, 31, v4
	v_readlane_b32 s8, v255, 41
	v_lshlrev_b64 v[4:5], 11, v[4:5]
	v_readlane_b32 s9, v255, 42
	s_lshl_b32 s20, s14, 8
	v_lshlrev_b32_e32 v50, 1, v73
	v_lshl_add_u64 v[4:5], s[8:9], 0, v[4:5]
	v_lshl_add_u64 v[4:5], v[4:5], 0, s[20:21]
	v_mov_b32_e32 v51, v1
	v_lshl_add_u64 v[4:5], v[4:5], 0, v[50:51]
	global_load_dwordx4 v[14:17], v[4:5], off offset:1024
	v_add_u32_e32 v4, 0x200, v68
	v_ashrrev_i32_e32 v71, 4, v4
	v_lshlrev_b32_e32 v4, 7, v71
	v_ashrrev_i32_e32 v5, 31, v4
	v_lshl_add_u64 v[4:5], v[4:5], 2, v[2:3]
	global_load_dwordx4 v[26:29], v[4:5], off offset:16
	global_load_dwordx4 v[30:33], v[4:5], off
	v_add_u32_e32 v4, s11, v71
	v_ashrrev_i32_e32 v5, 31, v4
	v_lshlrev_b64 v[4:5], 11, v[4:5]
	v_lshl_add_u64 v[4:5], s[8:9], 0, v[4:5]
	v_lshl_add_u64 v[4:5], v[4:5], 0, s[20:21]
	v_lshl_add_u64 v[4:5], v[4:5], 0, v[50:51]
	global_load_dwordx4 v[10:13], v[4:5], off offset:1024
	v_add_u32_e32 v4, 0x400, v68
	v_ashrrev_i32_e32 v70, 4, v4
	v_lshlrev_b32_e32 v4, 7, v70
	v_ashrrev_i32_e32 v5, 31, v4
	v_lshl_add_u64 v[4:5], v[4:5], 2, v[2:3]
	global_load_dwordx4 v[34:37], v[4:5], off offset:16
	global_load_dwordx4 v[38:41], v[4:5], off
	v_add_u32_e32 v4, s11, v70
	v_ashrrev_i32_e32 v5, 31, v4
	v_lshlrev_b64 v[4:5], 11, v[4:5]
	v_lshl_add_u64 v[4:5], s[8:9], 0, v[4:5]
	v_lshl_add_u64 v[4:5], v[4:5], 0, s[20:21]
	v_lshl_add_u64 v[4:5], v[4:5], 0, v[50:51]
	global_load_dwordx4 v[6:9], v[4:5], off offset:1024
	v_add_u32_e32 v4, 0x600, v68
	v_ashrrev_i32_e32 v69, 4, v4
	v_lshlrev_b32_e32 v4, 7, v69
	v_ashrrev_i32_e32 v5, 31, v4
	v_lshl_add_u64 v[2:3], v[4:5], 2, v[2:3]
	global_load_dwordx4 v[42:45], v[2:3], off offset:16
	global_load_dwordx4 v[46:49], v[2:3], off
	v_add_u32_e32 v2, s11, v69
	v_ashrrev_i32_e32 v3, 31, v2
	v_lshlrev_b64 v[2:3], 11, v[2:3]
	v_lshl_add_u64 v[2:3], s[8:9], 0, v[2:3]
	v_lshl_add_u64 v[2:3], v[2:3], 0, s[20:21]
	v_ashrrev_i32_e32 v72, 2, v68
	v_lshl_add_u64 v[2:3], v[2:3], 0, v[50:51]
	v_add_u32_e32 v50, s11, v72
	v_ashrrev_i32_e32 v51, 31, v50
	v_and_b32_e32 v75, 3, v68
	v_lshlrev_b64 v[50:51], 11, v[50:51]
	v_lshl_add_u64 v[50:51], s[8:9], 0, v[50:51]
	v_lshlrev_b32_e32 v52, 8, v75
	v_mov_b32_e32 v53, v1
	v_lshl_add_u64 v[66:67], v[50:51], 0, v[52:53]
	global_load_dwordx4 v[2:5], v[2:3], off offset:1024
	s_nop 0
	global_load_dwordx4 v[80:83], v[66:67], off offset:1072
	global_load_dwordx4 v[84:87], v[66:67], off offset:1056
	global_load_dwordx4 v[88:91], v[66:67], off offset:1040
	global_load_dwordx4 v[92:95], v[66:67], off offset:1024
	global_load_dwordx4 v[96:99], v[66:67], off offset:1136
	global_load_dwordx4 v[100:103], v[66:67], off offset:1120
	global_load_dwordx4 v[104:107], v[66:67], off offset:1104
	global_load_dwordx4 v[108:111], v[66:67], off offset:1088
	global_load_dwordx4 v[112:115], v[66:67], off offset:1200
	global_load_dwordx4 v[116:119], v[66:67], off offset:1184
	global_load_dwordx4 v[120:123], v[66:67], off offset:1168
	global_load_dwordx4 v[124:127], v[66:67], off offset:1152
	global_load_dwordx4 v[128:131], v[66:67], off offset:1264
	global_load_dwordx4 v[132:135], v[66:67], off offset:1248
	global_load_dwordx4 v[136:139], v[66:67], off offset:1232
	global_load_dwordx4 v[140:143], v[66:67], off offset:1216
	v_cmp_lt_i32_e32 vcc, v221, v220
	s_lshl_b32 s7, s14, 7
	v_readlane_b32 s42, v255, 38
	v_readlane_b32 s43, v255, 39
	s_lshl_b64 s[42:43], s[42:43], 2
	s_waitcnt lgkmcnt(0)
	s_add_u32 s98, s98, s42
	s_addc_u32 s99, s99, s43
	s_lshl_b32 s42, s7, 2
	s_add_u32 s98, s98, s42
	s_addc_u32 s99, s99, 0
	global_load_dwordx4 v[168:171], v0, s[98:99]
	global_load_dwordx4 v[172:175], v0, s[98:99] offset:16
	s_nop 0
	s_nop 0
	s_nop 0
	s_nop 0
	s_nop 0
	s_waitcnt vmcnt(14)
	v_lshlrev_b32_e32 v76, 16, v92
	v_and_b32_e32 v92, 0xffff0000, v92
	v_add_f32_e32 v77, v76, v92
	v_mul_f32_e32 v92, v92, v92
	v_fmac_f32_e32 v92, v76, v76
	v_lshlrev_b32_e32 v76, 16, v93
	v_and_b32_e32 v93, 0xffff0000, v93
	v_add_f32_e32 v78, v76, v93
	v_mul_f32_e32 v93, v93, v93
	v_fmac_f32_e32 v93, v76, v76
	v_add_f32_e32 v92, v92, v93
	v_lshlrev_b32_e32 v93, 16, v94
	v_and_b32_e32 v94, 0xffff0000, v94
	v_add_f32_e32 v76, v93, v94
	v_mul_f32_e32 v94, v94, v94
	v_fmac_f32_e32 v94, v93, v93
	v_add_f32_e32 v92, v94, v92
	v_lshlrev_b32_e32 v93, 16, v95
	v_and_b32_e32 v94, 0xffff0000, v95
	v_add_f32_e32 v95, v93, v94
	v_mul_f32_e32 v94, v94, v94
	v_fmac_f32_e32 v94, v93, v93
	v_lshlrev_b32_e32 v93, 16, v88
	v_and_b32_e32 v88, 0xffff0000, v88
	v_add_f32_e32 v92, v94, v92
	v_add_f32_e32 v94, v93, v88
	v_mul_f32_e32 v88, v88, v88
	v_fmac_f32_e32 v88, v93, v93
	v_add_f32_e32 v88, v88, v92
	v_lshlrev_b32_e32 v92, 16, v89
	v_and_b32_e32 v89, 0xffff0000, v89
	v_add_f32_e32 v93, v92, v89
	v_mul_f32_e32 v89, v89, v89
	v_fmac_f32_e32 v89, v92, v92
	v_add_f32_e32 v88, v89, v88
	v_lshlrev_b32_e32 v89, 16, v90
	v_and_b32_e32 v90, 0xffff0000, v90
	v_add_f32_e32 v92, v89, v90
	v_mul_f32_e32 v90, v90, v90
	v_fmac_f32_e32 v90, v89, v89
	v_add_f32_e32 v88, v90, v88
	v_lshlrev_b32_e32 v89, 16, v91
	v_and_b32_e32 v90, 0xffff0000, v91
	v_add_f32_e32 v91, v89, v90
	v_mul_f32_e32 v90, v90, v90
	v_fmac_f32_e32 v90, v89, v89
	v_lshlrev_b32_e32 v89, 16, v84
	v_and_b32_e32 v84, 0xffff0000, v84
	v_add_f32_e32 v88, v90, v88
	v_add_f32_e32 v90, v89, v84
	v_mul_f32_e32 v84, v84, v84
	v_fmac_f32_e32 v84, v89, v89
	v_add_f32_e32 v84, v84, v88
	v_lshlrev_b32_e32 v88, 16, v85
	v_and_b32_e32 v85, 0xffff0000, v85
	v_add_f32_e32 v89, v88, v85
	v_mul_f32_e32 v85, v85, v85
	v_fmac_f32_e32 v85, v88, v88
	v_add_f32_e32 v84, v85, v84
	v_lshlrev_b32_e32 v85, 16, v86
	v_and_b32_e32 v86, 0xffff0000, v86
	v_add_f32_e32 v88, v85, v86
	v_mul_f32_e32 v86, v86, v86
	v_add_f32_e32 v77, 0, v77
	v_fmac_f32_e32 v86, v85, v85
	v_add_f32_e32 v77, v78, v77
	v_add_f32_e32 v84, v86, v84
	v_lshlrev_b32_e32 v85, 16, v87
	v_and_b32_e32 v86, 0xffff0000, v87
	v_add_f32_e32 v76, v76, v77
	v_add_f32_e32 v87, v85, v86
	v_mul_f32_e32 v86, v86, v86
	v_add_f32_e32 v95, v95, v76
	v_fmac_f32_e32 v86, v85, v85
	v_lshlrev_b32_e32 v85, 16, v80
	v_and_b32_e32 v80, 0xffff0000, v80
	v_add_f32_e32 v94, v94, v95
	v_add_f32_e32 v84, v86, v84
	v_add_f32_e32 v86, v85, v80
	v_mul_f32_e32 v80, v80, v80
	v_add_f32_e32 v93, v93, v94
	v_fmac_f32_e32 v80, v85, v85
	v_add_f32_e32 v92, v92, v93
	v_add_f32_e32 v80, v80, v84
	v_lshlrev_b32_e32 v84, 16, v81
	v_and_b32_e32 v81, 0xffff0000, v81
	v_add_f32_e32 v91, v91, v92
	v_add_f32_e32 v85, v84, v81
	v_mul_f32_e32 v81, v81, v81
	v_add_f32_e32 v90, v90, v91
	v_fmac_f32_e32 v81, v84, v84
	v_add_f32_e32 v89, v89, v90
	v_add_f32_e32 v80, v81, v80
	v_lshlrev_b32_e32 v81, 16, v82
	v_and_b32_e32 v82, 0xffff0000, v82
	v_add_f32_e32 v88, v88, v89
	v_add_f32_e32 v84, v81, v82
	v_mul_f32_e32 v82, v82, v82
	v_add_f32_e32 v87, v87, v88
	v_fmac_f32_e32 v82, v81, v81
	v_add_f32_e32 v86, v86, v87
	v_add_f32_e32 v80, v82, v80
	v_lshlrev_b32_e32 v81, 16, v83
	v_and_b32_e32 v82, 0xffff0000, v83
	v_add_f32_e32 v85, v85, v86
	v_add_f32_e32 v83, v81, v82
	v_mul_f32_e32 v82, v82, v82
	v_add_f32_e32 v84, v84, v85
	v_fmac_f32_e32 v82, v81, v81
	v_add_f32_e32 v77, v83, v84
	v_add_f32_e32 v76, v82, v80
	s_waitcnt vmcnt(10)
	v_lshlrev_b32_e32 v78, 16, v108
	v_and_b32_e32 v108, 0xffff0000, v108
	v_add_f32_e32 v79, v78, v108
	v_mul_f32_e32 v108, v108, v108
	v_fmac_f32_e32 v108, v78, v78
	v_add_f32_e32 v108, v108, v76
	v_lshlrev_b32_e32 v76, 16, v109
	v_and_b32_e32 v109, 0xffff0000, v109
	v_add_f32_e32 v78, v76, v109
	v_mul_f32_e32 v109, v109, v109
	v_fmac_f32_e32 v109, v76, v76
	v_add_f32_e32 v108, v109, v108
	v_lshlrev_b32_e32 v109, 16, v110
	v_and_b32_e32 v110, 0xffff0000, v110
	v_add_f32_e32 v76, v109, v110
	v_mul_f32_e32 v110, v110, v110
	v_fmac_f32_e32 v110, v109, v109
	v_add_f32_e32 v108, v110, v108
	v_lshlrev_b32_e32 v109, 16, v111
	v_and_b32_e32 v110, 0xffff0000, v111
	v_add_f32_e32 v111, v109, v110
	v_mul_f32_e32 v110, v110, v110
	v_fmac_f32_e32 v110, v109, v109
	v_lshlrev_b32_e32 v109, 16, v104
	v_and_b32_e32 v104, 0xffff0000, v104
	v_add_f32_e32 v108, v110, v108
	v_add_f32_e32 v110, v109, v104
	v_mul_f32_e32 v104, v104, v104
	v_fmac_f32_e32 v104, v109, v109
	v_add_f32_e32 v104, v104, v108
	v_lshlrev_b32_e32 v108, 16, v105
	v_and_b32_e32 v105, 0xffff0000, v105
	v_add_f32_e32 v109, v108, v105
	v_mul_f32_e32 v105, v105, v105
	v_fmac_f32_e32 v105, v108, v108
	v_add_f32_e32 v104, v105, v104
	v_lshlrev_b32_e32 v105, 16, v106
	v_and_b32_e32 v106, 0xffff0000, v106
	v_add_f32_e32 v108, v105, v106
	v_mul_f32_e32 v106, v106, v106
	v_fmac_f32_e32 v106, v105, v105
	v_add_f32_e32 v104, v106, v104
	v_lshlrev_b32_e32 v105, 16, v107
	v_and_b32_e32 v106, 0xffff0000, v107
	v_add_f32_e32 v107, v105, v106
	v_mul_f32_e32 v106, v106, v106
	v_fmac_f32_e32 v106, v105, v105
	v_lshlrev_b32_e32 v105, 16, v100
	v_and_b32_e32 v100, 0xffff0000, v100
	v_add_f32_e32 v104, v106, v104
	v_add_f32_e32 v106, v105, v100
	v_mul_f32_e32 v100, v100, v100
	v_fmac_f32_e32 v100, v105, v105
	v_add_f32_e32 v100, v100, v104
	v_lshlrev_b32_e32 v104, 16, v101
	v_and_b32_e32 v101, 0xffff0000, v101
	v_add_f32_e32 v105, v104, v101
	v_mul_f32_e32 v101, v101, v101
	v_fmac_f32_e32 v101, v104, v104
	v_add_f32_e32 v100, v101, v100
	v_lshlrev_b32_e32 v101, 16, v102
	v_and_b32_e32 v102, 0xffff0000, v102
	v_add_f32_e32 v104, v101, v102
	v_mul_f32_e32 v102, v102, v102
	v_add_f32_e32 v77, v79, v77
	v_fmac_f32_e32 v102, v101, v101
	v_add_f32_e32 v77, v78, v77
	v_add_f32_e32 v100, v102, v100
	v_lshlrev_b32_e32 v101, 16, v103
	v_and_b32_e32 v102, 0xffff0000, v103
	v_add_f32_e32 v76, v76, v77
	v_add_f32_e32 v103, v101, v102
	v_mul_f32_e32 v102, v102, v102
	v_add_f32_e32 v111, v111, v76
	v_fmac_f32_e32 v102, v101, v101
	v_lshlrev_b32_e32 v101, 16, v96
	v_and_b32_e32 v96, 0xffff0000, v96
	v_add_f32_e32 v110, v110, v111
	v_add_f32_e32 v100, v102, v100
	v_add_f32_e32 v102, v101, v96
	v_mul_f32_e32 v96, v96, v96
	v_add_f32_e32 v109, v109, v110
	v_fmac_f32_e32 v96, v101, v101
	v_add_f32_e32 v108, v108, v109
	v_add_f32_e32 v96, v96, v100
	v_lshlrev_b32_e32 v100, 16, v97
	v_and_b32_e32 v97, 0xffff0000, v97
	v_add_f32_e32 v107, v107, v108
	v_add_f32_e32 v101, v100, v97
	v_mul_f32_e32 v97, v97, v97
	v_add_f32_e32 v106, v106, v107
	v_fmac_f32_e32 v97, v100, v100
	v_add_f32_e32 v105, v105, v106
	v_add_f32_e32 v96, v97, v96
	v_lshlrev_b32_e32 v97, 16, v98
	v_and_b32_e32 v98, 0xffff0000, v98
	v_add_f32_e32 v104, v104, v105
	v_add_f32_e32 v100, v97, v98
	v_mul_f32_e32 v98, v98, v98
	v_add_f32_e32 v103, v103, v104
	v_fmac_f32_e32 v98, v97, v97
	v_add_f32_e32 v102, v102, v103
	v_add_f32_e32 v96, v98, v96
	v_lshlrev_b32_e32 v97, 16, v99
	v_and_b32_e32 v98, 0xffff0000, v99
	v_add_f32_e32 v101, v101, v102
	v_add_f32_e32 v99, v97, v98
	v_mul_f32_e32 v98, v98, v98
	v_add_f32_e32 v100, v100, v101
	v_fmac_f32_e32 v98, v97, v97
	v_add_f32_e32 v77, v99, v100
	v_add_f32_e32 v76, v98, v96
	s_waitcnt vmcnt(6)
	v_lshlrev_b32_e32 v78, 16, v124
	v_and_b32_e32 v124, 0xffff0000, v124
	v_add_f32_e32 v79, v78, v124
	v_mul_f32_e32 v124, v124, v124
	v_fmac_f32_e32 v124, v78, v78
	v_add_f32_e32 v124, v124, v76
	v_lshlrev_b32_e32 v76, 16, v125
	v_and_b32_e32 v125, 0xffff0000, v125
	v_add_f32_e32 v78, v76, v125
	v_mul_f32_e32 v125, v125, v125
	v_fmac_f32_e32 v125, v76, v76
	v_add_f32_e32 v124, v125, v124
	v_lshlrev_b32_e32 v125, 16, v126
	v_and_b32_e32 v126, 0xffff0000, v126
	v_add_f32_e32 v76, v125, v126
	v_mul_f32_e32 v126, v126, v126
	v_fmac_f32_e32 v126, v125, v125
	v_add_f32_e32 v124, v126, v124
	v_lshlrev_b32_e32 v125, 16, v127
	v_and_b32_e32 v126, 0xffff0000, v127
	v_add_f32_e32 v127, v125, v126
	v_mul_f32_e32 v126, v126, v126
	v_fmac_f32_e32 v126, v125, v125
	v_lshlrev_b32_e32 v125, 16, v120
	v_and_b32_e32 v120, 0xffff0000, v120
	v_add_f32_e32 v124, v126, v124
	v_add_f32_e32 v126, v125, v120
	v_mul_f32_e32 v120, v120, v120
	v_fmac_f32_e32 v120, v125, v125
	v_add_f32_e32 v120, v120, v124
	v_lshlrev_b32_e32 v124, 16, v121
	v_and_b32_e32 v121, 0xffff0000, v121
	v_add_f32_e32 v125, v124, v121
	v_mul_f32_e32 v121, v121, v121
	v_fmac_f32_e32 v121, v124, v124
	v_add_f32_e32 v120, v121, v120
	v_lshlrev_b32_e32 v121, 16, v122
	v_and_b32_e32 v122, 0xffff0000, v122
	v_add_f32_e32 v124, v121, v122
	v_mul_f32_e32 v122, v122, v122
	v_fmac_f32_e32 v122, v121, v121
	v_add_f32_e32 v120, v122, v120
	v_lshlrev_b32_e32 v121, 16, v123
	v_and_b32_e32 v122, 0xffff0000, v123
	v_add_f32_e32 v123, v121, v122
	v_mul_f32_e32 v122, v122, v122
	v_fmac_f32_e32 v122, v121, v121
	v_lshlrev_b32_e32 v121, 16, v116
	v_and_b32_e32 v116, 0xffff0000, v116
	v_add_f32_e32 v120, v122, v120
	v_add_f32_e32 v122, v121, v116
	v_mul_f32_e32 v116, v116, v116
	v_fmac_f32_e32 v116, v121, v121
	v_add_f32_e32 v116, v116, v120
	v_lshlrev_b32_e32 v120, 16, v117
	v_and_b32_e32 v117, 0xffff0000, v117
	v_add_f32_e32 v121, v120, v117
	v_mul_f32_e32 v117, v117, v117
	v_fmac_f32_e32 v117, v120, v120
	v_add_f32_e32 v116, v117, v116
	v_lshlrev_b32_e32 v117, 16, v118
	v_and_b32_e32 v118, 0xffff0000, v118
	v_add_f32_e32 v120, v117, v118
	v_mul_f32_e32 v118, v118, v118
	v_add_f32_e32 v77, v79, v77
	v_fmac_f32_e32 v118, v117, v117
	v_add_f32_e32 v77, v78, v77
	v_add_f32_e32 v116, v118, v116
	v_lshlrev_b32_e32 v117, 16, v119
	v_and_b32_e32 v118, 0xffff0000, v119
	v_add_f32_e32 v76, v76, v77
	v_add_f32_e32 v119, v117, v118
	v_mul_f32_e32 v118, v118, v118
	v_add_f32_e32 v127, v127, v76
	v_fmac_f32_e32 v118, v117, v117
	v_lshlrev_b32_e32 v117, 16, v112
	v_and_b32_e32 v112, 0xffff0000, v112
	v_add_f32_e32 v126, v126, v127
	v_add_f32_e32 v116, v118, v116
	v_add_f32_e32 v118, v117, v112
	v_mul_f32_e32 v112, v112, v112
	v_add_f32_e32 v125, v125, v126
	v_fmac_f32_e32 v112, v117, v117
	v_add_f32_e32 v124, v124, v125
	v_add_f32_e32 v112, v112, v116
	v_lshlrev_b32_e32 v116, 16, v113
	v_and_b32_e32 v113, 0xffff0000, v113
	v_add_f32_e32 v123, v123, v124
	v_add_f32_e32 v117, v116, v113
	v_mul_f32_e32 v113, v113, v113
	v_add_f32_e32 v122, v122, v123
	v_fmac_f32_e32 v113, v116, v116
	v_add_f32_e32 v121, v121, v122
	v_add_f32_e32 v112, v113, v112
	v_lshlrev_b32_e32 v113, 16, v114
	v_and_b32_e32 v114, 0xffff0000, v114
	v_add_f32_e32 v120, v120, v121
	v_add_f32_e32 v116, v113, v114
	v_mul_f32_e32 v114, v114, v114
	v_add_f32_e32 v119, v119, v120
	v_fmac_f32_e32 v114, v113, v113
	v_add_f32_e32 v118, v118, v119
	v_add_f32_e32 v112, v114, v112
	v_lshlrev_b32_e32 v113, 16, v115
	v_and_b32_e32 v114, 0xffff0000, v115
	v_add_f32_e32 v117, v117, v118
	v_add_f32_e32 v115, v113, v114
	v_mul_f32_e32 v114, v114, v114
	v_add_f32_e32 v116, v116, v117
	v_fmac_f32_e32 v114, v113, v113
	v_add_f32_e32 v77, v115, v116
	v_add_f32_e32 v76, v114, v112
	s_waitcnt vmcnt(2)
	v_lshlrev_b32_e32 v66, 16, v140
	v_and_b32_e32 v140, 0xffff0000, v140
	v_add_f32_e32 v67, v66, v140
	v_mul_f32_e32 v140, v140, v140
	v_fmac_f32_e32 v140, v66, v66
	v_lshlrev_b32_e32 v66, 16, v141
	v_and_b32_e32 v141, 0xffff0000, v141
	v_add_f32_e32 v140, v140, v76
	v_add_f32_e32 v76, v66, v141
	v_mul_f32_e32 v141, v141, v141
	v_fmac_f32_e32 v141, v66, v66
	v_add_f32_e32 v140, v141, v140
	v_lshlrev_b32_e32 v141, 16, v142
	v_and_b32_e32 v142, 0xffff0000, v142
	v_add_f32_e32 v66, v141, v142
	v_mul_f32_e32 v142, v142, v142
	v_fmac_f32_e32 v142, v141, v141
	v_add_f32_e32 v140, v142, v140
	v_lshlrev_b32_e32 v141, 16, v143
	v_and_b32_e32 v142, 0xffff0000, v143
	v_add_f32_e32 v143, v141, v142
	v_mul_f32_e32 v142, v142, v142
	v_fmac_f32_e32 v142, v141, v141
	v_lshlrev_b32_e32 v141, 16, v136
	v_and_b32_e32 v136, 0xffff0000, v136
	v_add_f32_e32 v140, v142, v140
	v_add_f32_e32 v142, v141, v136
	v_mul_f32_e32 v136, v136, v136
	v_fmac_f32_e32 v136, v141, v141
	v_add_f32_e32 v136, v136, v140
	v_lshlrev_b32_e32 v140, 16, v137
	v_and_b32_e32 v137, 0xffff0000, v137
	v_add_f32_e32 v141, v140, v137
	v_mul_f32_e32 v137, v137, v137
	v_fmac_f32_e32 v137, v140, v140
	v_add_f32_e32 v136, v137, v136
	v_lshlrev_b32_e32 v137, 16, v138
	v_and_b32_e32 v138, 0xffff0000, v138
	v_add_f32_e32 v140, v137, v138
	v_mul_f32_e32 v138, v138, v138
	v_fmac_f32_e32 v138, v137, v137
	v_add_f32_e32 v136, v138, v136
	v_lshlrev_b32_e32 v137, 16, v139
	v_and_b32_e32 v138, 0xffff0000, v139
	v_add_f32_e32 v139, v137, v138
	v_mul_f32_e32 v138, v138, v138
	v_fmac_f32_e32 v138, v137, v137
	v_lshlrev_b32_e32 v137, 16, v132
	v_and_b32_e32 v132, 0xffff0000, v132
	v_add_f32_e32 v136, v138, v136
	v_add_f32_e32 v138, v137, v132
	v_mul_f32_e32 v132, v132, v132
	v_fmac_f32_e32 v132, v137, v137
	v_add_f32_e32 v132, v132, v136
	v_lshlrev_b32_e32 v136, 16, v133
	v_and_b32_e32 v133, 0xffff0000, v133
	v_add_f32_e32 v137, v136, v133
	v_mul_f32_e32 v133, v133, v133
	v_fmac_f32_e32 v133, v136, v136
	v_add_f32_e32 v132, v133, v132
	v_lshlrev_b32_e32 v133, 16, v134
	v_and_b32_e32 v134, 0xffff0000, v134
	v_add_f32_e32 v136, v133, v134
	v_mul_f32_e32 v134, v134, v134
	v_fmac_f32_e32 v134, v133, v133
	v_add_f32_e32 v67, v67, v77
	v_add_f32_e32 v132, v134, v132
	v_lshlrev_b32_e32 v133, 16, v135
	v_and_b32_e32 v134, 0xffff0000, v135
	v_add_f32_e32 v67, v76, v67
	v_add_f32_e32 v135, v133, v134
	v_mul_f32_e32 v134, v134, v134
	v_add_f32_e32 v66, v66, v67
	v_fmac_f32_e32 v134, v133, v133
	v_lshlrev_b32_e32 v133, 16, v128
	v_and_b32_e32 v128, 0xffff0000, v128
	v_add_f32_e32 v143, v143, v66
	v_add_f32_e32 v132, v134, v132
	v_add_f32_e32 v134, v133, v128
	v_mul_f32_e32 v128, v128, v128
	v_add_f32_e32 v142, v142, v143
	v_fmac_f32_e32 v128, v133, v133
	v_add_f32_e32 v141, v141, v142
	v_add_f32_e32 v128, v128, v132
	v_lshlrev_b32_e32 v132, 16, v129
	v_and_b32_e32 v129, 0xffff0000, v129
	v_add_f32_e32 v140, v140, v141
	v_add_f32_e32 v133, v132, v129
	v_mul_f32_e32 v129, v129, v129
	v_add_f32_e32 v139, v139, v140
	v_fmac_f32_e32 v129, v132, v132
	v_add_f32_e32 v138, v138, v139
	v_add_f32_e32 v128, v129, v128
	v_lshlrev_b32_e32 v129, 16, v130
	v_and_b32_e32 v130, 0xffff0000, v130
	v_add_f32_e32 v137, v137, v138
	v_add_f32_e32 v132, v129, v130
	v_mul_f32_e32 v130, v130, v130
	v_add_f32_e32 v136, v136, v137
	v_fmac_f32_e32 v130, v129, v129
	v_add_f32_e32 v135, v135, v136
	v_add_f32_e32 v128, v130, v128
	v_lshlrev_b32_e32 v129, 16, v131
	v_and_b32_e32 v130, 0xffff0000, v131
	v_add_f32_e32 v134, v134, v135
	v_add_f32_e32 v131, v129, v130
	v_mul_f32_e32 v130, v130, v130
	v_add_f32_e32 v133, v133, v134
	v_fmac_f32_e32 v130, v129, v129
	v_add_f32_e32 v132, v132, v133
	v_add_f32_e32 v130, v130, v128
	v_cndmask_b32_e32 v128, v218, v221, vcc
	v_add_f32_e32 v131, v131, v132
	v_lshlrev_b32_e32 v132, 2, v128
	ds_bpermute_b32 v128, v132, v131
	ds_bpermute_b32 v132, v132, v130
	v_cmp_lt_i32_e32 vcc, v222, v220
	s_waitcnt lgkmcnt(1)
	v_add_f32_e32 v128, v131, v128
	v_cndmask_b32_e32 v129, v218, v222, vcc
	v_lshlrev_b32_e32 v131, 2, v129
	s_waitcnt lgkmcnt(0)
	v_add_f32_e32 v130, v130, v132
	ds_bpermute_b32 v129, v131, v128
	ds_bpermute_b32 v131, v131, v130
	v_cmp_eq_u32_e32 vcc, 0, v75
	s_and_saveexec_b64 s[8:9], vcc
	s_cbranch_execz .LBB0_249
	s_waitcnt lgkmcnt(1)
	v_add_f32_e32 v128, v128, v129
	v_mul_f32_e32 v128, 0x3b000000, v128
	s_waitcnt lgkmcnt(0)
	v_add_f32_e32 v130, v130, v131
	v_mul_f32_e32 v129, v128, v128
	s_mov_b32 s12, 0x3b000000
	v_fma_f32 v129, v130, s12, -v129
	v_max_f32_e32 v129, 0, v129
	v_add_f32_e32 v129, 0x358637bd, v129
	v_mul_f32_e32 v130, 0x4f800000, v129
	v_cmp_gt_f32_e32 vcc, s23, v129
	s_nop 1
	v_cndmask_b32_e32 v129, v129, v130, vcc
	v_sqrt_f32_e32 v130, v129
	s_nop 0
	v_add_u32_e32 v131, -1, v130
	v_fma_f32 v132, -v131, v130, v129
	v_cmp_ge_f32_e64 s[42:43], 0, v132
	v_add_u32_e32 v132, 1, v130
	s_nop 0
	v_cndmask_b32_e64 v131, v130, v131, s[42:43]
	v_fma_f32 v130, -v132, v130, v129
	v_cmp_lt_f32_e64 s[42:43], 0, v130
	s_nop 1
	v_cndmask_b32_e64 v130, v131, v132, s[42:43]
	v_mul_f32_e32 v131, 0x37800000, v130
	v_cndmask_b32_e32 v130, v130, v131, vcc
	v_cmp_class_f32_e32 vcc, v129, v210
	v_lshl_add_u32 v132, v72, 2, 0
	v_add_u32_e32 v132, 0x20000, v132
	v_cndmask_b32_e32 v129, v130, v129, vcc
	v_div_scale_f32 v130, s[12:13], v129, v129, 1.0
	v_rcp_f32_e32 v131, v130
	s_nop 0
	v_fma_f32 v133, -v130, v131, 1.0
	v_fmac_f32_e32 v131, v133, v131
	v_div_scale_f32 v133, vcc, 1.0, v129, 1.0
	v_mul_f32_e32 v134, v133, v131
	v_fma_f32 v135, -v130, v134, v133
	v_fmac_f32_e32 v134, v135, v131
	v_fma_f32 v130, -v130, v134, v133
	v_div_fmas_f32 v130, v130, v131, v134
	v_div_fixup_f32 v129, v130, v129, 1.0
	ds_write2st64_b32 v132, v128, v129 offset1:2
.LBB0_249:
	s_or_b64 exec, exec, s[8:9]
	v_lshl_add_u32 v50, v73, 1, 0
	s_movk_i32 s14, 0x110
	v_cvt_pk_bf16_f32 v22, v22, v23
	v_cvt_pk_bf16_f32 v23, v24, v25
	v_cvt_pk_bf16_f32 v24, v18, v19
	s_waitcnt lgkmcnt(1)
	v_mad_u64_u32 v[18:19], s[8:9], v74, s14, v[50:51]
	v_cvt_pk_bf16_f32 v25, v20, v21
	ds_write_b128 v18, v[22:25]
	v_mad_u64_u32 v[22:23], s[8:9], v71, s14, v[50:51]
	v_cvt_pk_bf16_f32 v18, v30, v31
	v_cvt_pk_bf16_f32 v19, v32, v33
	v_cvt_pk_bf16_f32 v20, v26, v27
	v_cvt_pk_bf16_f32 v21, v28, v29
	ds_write_b128 v22, v[18:21]
	v_mad_u64_u32 v[22:23], s[8:9], v70, s14, v[50:51]
	v_cvt_pk_bf16_f32 v18, v38, v39
	v_cvt_pk_bf16_f32 v19, v40, v41
	v_cvt_pk_bf16_f32 v20, v34, v35
	v_cvt_pk_bf16_f32 v21, v36, v37
	ds_write_b128 v22, v[18:21]
	v_mad_u64_u32 v[22:23], s[8:9], v69, s14, v[50:51]
	v_cvt_pk_bf16_f32 v18, v46, v47
	v_cvt_pk_bf16_f32 v19, v48, v49
	v_cvt_pk_bf16_f32 v20, v42, v43
	v_cvt_pk_bf16_f32 v21, v44, v45
	ds_write_b128 v22, v[18:21]
	s_waitcnt lgkmcnt(0)
	s_barrier
	v_readlane_b32 s16, v255, 38
	v_readlane_b32 s17, v255, 39
	s_lshl_b64 s[12:13], s[16:17], 2
	v_and_b32_e32 v26, 0xffff0000, v14
	s_waitcnt lgkmcnt(0)
	s_add_u32 s8, s8, s12
	s_addc_u32 s9, s9, s13
	s_lshl_b32 s12, s7, 2
	s_add_u32 s8, s8, s12
	s_addc_u32 s9, s9, 0
	v_and_b32_e32 v156, 15, v68
	v_bfe_u32 v157, v68, 4, 2
	v_and_b32_e32 v158, -16, v72
	v_lshl_or_b32 v158, v157, 2, v158
	v_ashrrev_i32_e32 v159, 31, v158
	v_mov_b32_e32 v160, s20
	v_mov_b32_e32 v161, 0
	v_lshl_add_u64 v[162:163], v[158:159], 1, v[160:161]
	s_add_i32 s98, s11, 16
	v_add_lshl_u32 v160, s98, v156, 11
	v_lshl_add_u64 v[164:165], v[162:163], 0, v[160:161]
	s_lshl_b32 s98, s10, 16
	s_and_b32 s98, s98, 0x3fc0000
	v_lshl_or_b32 v160, v156, 11, s98
	v_lshl_add_u64 v[162:163], v[162:163], 0, v[160:161]
	v_lshl_add_u64 v[164:165], s[64:65], 0, v[164:165]
	v_lshl_add_u64 v[162:163], s[64:65], 0, v[162:163]
	s_add_i32 s98, s16, s7
	v_add_u32_e32 v166, s98, v156
	v_ashrrev_i32_e32 v167, 31, v166
	v_lshl_add_u64 v[166:167], v[166:167], 2, s[100:101]
	global_load_dword v80, v[166:167], off
	global_load_dword v81, v[166:167], off offset:64
	global_load_dword v82, v[166:167], off offset:128
	global_load_dword v83, v[166:167], off offset:192
	global_load_dword v84, v[166:167], off offset:256
	global_load_dword v85, v[166:167], off offset:320
	global_load_dword v86, v[166:167], off offset:384
	global_load_dword v87, v[166:167], off offset:448
	s_mov_b32 s98, 0xc200000
	s_mov_b32 s99, 0
	v_lshl_add_u64 v[160:161], v[162:163], 0, s[98:99]
	global_load_dwordx2 v[88:89], v[160:161], off
	v_lshl_add_u64 v[160:161], v[164:165], 0, s[98:99]
	global_load_dwordx2 v[90:91], v[160:161], off
	s_add_u32 s98, s98, 0x10000
	v_lshl_add_u64 v[160:161], v[162:163], 0, s[98:99]
	global_load_dwordx2 v[92:93], v[160:161], off
	v_lshl_add_u64 v[160:161], v[164:165], 0, s[98:99]
	global_load_dwordx2 v[94:95], v[160:161], off
	s_add_u32 s98, s98, 0x10000
	v_lshl_add_u64 v[160:161], v[162:163], 0, s[98:99]
	global_load_dwordx2 v[96:97], v[160:161], off
	v_lshl_add_u64 v[160:161], v[164:165], 0, s[98:99]
	global_load_dwordx2 v[98:99], v[160:161], off
	s_add_u32 s98, s98, 0x10000
	v_lshl_add_u64 v[160:161], v[162:163], 0, s[98:99]
	global_load_dwordx2 v[100:101], v[160:161], off
	v_lshl_add_u64 v[160:161], v[164:165], 0, s[98:99]
	global_load_dwordx2 v[102:103], v[160:161], off
	s_nop 0
	s_nop 0
	s_add_i32 s12, 0, 0x20000
	v_lshlrev_b32_e32 v0, 16, v14
	v_lshl_add_u32 v14, v74, 2, s12
	v_lshlrev_b32_e32 v27, 16, v15
	v_and_b32_e32 v28, 0xffff0000, v15
	ds_read2st64_b32 v[14:15], v14 offset1:2
	v_lshlrev_b32_e32 v29, 16, v16
	v_and_b32_e32 v16, 0xffff0000, v16
	v_lshlrev_b32_e32 v30, 16, v17
	v_and_b32_e32 v17, 0xffff0000, v17
	s_waitcnt lgkmcnt(0)
	v_sub_f32_e32 v0, v0, v14
	v_sub_f32_e32 v26, v26, v14
	v_sub_f32_e32 v27, v27, v14
	v_sub_f32_e32 v28, v28, v14
	v_sub_f32_e32 v29, v29, v14
	v_sub_f32_e32 v16, v16, v14
	v_sub_f32_e32 v30, v30, v14
	v_sub_f32_e32 v14, v17, v14
	v_mul_f32_e32 v0, v15, v0
	v_mul_f32_e32 v17, v15, v26
	v_mul_f32_e32 v26, v15, v27
	v_mul_f32_e32 v27, v15, v28
	v_mul_f32_e32 v28, v15, v29
	v_mul_f32_e32 v16, v15, v16
	v_mul_f32_e32 v29, v15, v30
	v_mul_f32_e32 v14, v15, v14
	v_xor_b32_e32 v31, v74, v73
	v_lshlrev_b32_e32 v31, 1, v31
	v_mul_u32_u24_e32 v32, 0x110, v73
	v_add3_u32 v31, 0, v31, v32
	s_load_dwordx2 s[8:9], s[0:1], 0xb0
	s_add_i32 s11, s11, 16
	s_lshl_b32 s6, s6, 7
	s_waitcnt vmcnt(17)
	v_mul_f32_e32 v0, v168, v0
	v_mul_f32_e32 v15, v169, v17
	v_mul_f32_e32 v17, v170, v26
	v_mul_f32_e32 v26, v171, v27
	s_waitcnt vmcnt(16)
	v_mul_f32_e32 v27, v172, v28
	v_mul_f32_e32 v16, v173, v16
	v_mul_f32_e32 v28, v174, v29
	v_mul_f32_e32 v29, v175, v14
	v_bfe_u32 v14, v0, 16, 1
	v_bfe_u32 v30, v15, 16, 1
	v_bfe_u32 v33, v17, 16, 1
	v_bfe_u32 v34, v26, 16, 1
	v_bfe_u32 v35, v27, 16, 1
	v_bfe_u32 v36, v16, 16, 1
	v_add3_u32 v0, v0, v14, s90
	v_add3_u32 v14, v15, v30, s90
	v_add3_u32 v15, v17, v33, s90
	v_add3_u32 v17, v26, v34, s90
	v_add3_u32 v26, v27, v35, s90
	v_add3_u32 v16, v16, v36, s90
	ds_write_b16_d16_hi v31, v0 offset:34816
	ds_write_b16_d16_hi v31, v14 offset:35088
	ds_write_b16_d16_hi v31, v15 offset:35360
	ds_write_b16_d16_hi v31, v17 offset:35632
	ds_write_b16_d16_hi v31, v26 offset:35904
	ds_write_b16_d16_hi v31, v16 offset:36176
	v_bfe_u32 v0, v28, 16, 1
	v_add3_u32 v0, v28, v0, s90
	ds_write_b16_d16_hi v31, v0 offset:36448
	v_lshl_add_u32 v0, v71, 2, s12
	ds_read2st64_b32 v[14:15], v0 offset1:2
	v_bfe_u32 v0, v29, 16, 1
	v_add3_u32 v0, v29, v0, s90
	ds_write_b16_d16_hi v31, v0 offset:36720
	v_lshlrev_b32_e32 v0, 16, v10
	s_waitcnt lgkmcnt(0)
	v_sub_f32_e32 v0, v0, v14
	v_mul_f32_e32 v0, v15, v0
	v_and_b32_e32 v10, 0xffff0000, v10
	v_lshlrev_b32_e32 v16, 16, v11
	v_and_b32_e32 v11, 0xffff0000, v11
	v_lshlrev_b32_e32 v17, 16, v12
	v_and_b32_e32 v12, 0xffff0000, v12
	v_lshlrev_b32_e32 v26, 16, v13
	v_and_b32_e32 v13, 0xffff0000, v13
	v_mul_f32_e32 v0, v168, v0
	v_sub_f32_e32 v10, v10, v14
	v_sub_f32_e32 v16, v16, v14
	v_sub_f32_e32 v11, v11, v14
	v_sub_f32_e32 v17, v17, v14
	v_sub_f32_e32 v12, v12, v14
	v_sub_f32_e32 v26, v26, v14
	v_sub_f32_e32 v13, v13, v14
	v_mul_f32_e32 v10, v15, v10
	v_mul_f32_e32 v16, v15, v16
	v_mul_f32_e32 v11, v15, v11
	v_mul_f32_e32 v17, v15, v17
	v_mul_f32_e32 v12, v15, v12
	v_mul_f32_e32 v26, v15, v26
	v_mul_f32_e32 v13, v15, v13
	v_xor_b32_e32 v14, v71, v73
	v_lshlrev_b32_e32 v14, 1, v14
	v_bfe_u32 v15, v0, 16, 1
	v_mul_f32_e32 v10, v169, v10
	v_add3_u32 v0, v0, v15, s90
	v_add3_u32 v14, 0, v14, v32
	ds_write_b16_d16_hi v14, v0 offset:34816
	v_bfe_u32 v0, v10, 16, 1
	v_mul_f32_e32 v16, v170, v16
	v_add3_u32 v0, v10, v0, s90
	ds_write_b16_d16_hi v14, v0 offset:35088
	v_bfe_u32 v0, v16, 16, 1
	v_mul_f32_e32 v11, v171, v11
	v_add3_u32 v0, v16, v0, s90
	ds_write_b16_d16_hi v14, v0 offset:35360
	v_bfe_u32 v0, v11, 16, 1
	v_mul_f32_e32 v17, v172, v17
	v_add3_u32 v0, v11, v0, s90
	ds_write_b16_d16_hi v14, v0 offset:35632
	v_bfe_u32 v0, v17, 16, 1
	v_mul_f32_e32 v12, v173, v12
	v_add3_u32 v0, v17, v0, s90
	ds_write_b16_d16_hi v14, v0 offset:35904
	v_bfe_u32 v0, v12, 16, 1
	v_mul_f32_e32 v26, v174, v26
	v_add3_u32 v0, v12, v0, s90
	ds_write_b16_d16_hi v14, v0 offset:36176
	v_bfe_u32 v0, v26, 16, 1
	v_add3_u32 v0, v26, v0, s90
	ds_write_b16_d16_hi v14, v0 offset:36448
	v_lshl_add_u32 v0, v70, 2, s12
	ds_read2st64_b32 v[10:11], v0 offset1:2
	v_mul_f32_e32 v13, v175, v13
	v_bfe_u32 v0, v13, 16, 1
	v_add3_u32 v0, v13, v0, s90
	ds_write_b16_d16_hi v14, v0 offset:36720
	v_lshlrev_b32_e32 v0, 16, v6
	s_waitcnt lgkmcnt(1)
	v_sub_f32_e32 v0, v0, v10
	v_mul_f32_e32 v0, v11, v0
	v_and_b32_e32 v6, 0xffff0000, v6
	v_lshlrev_b32_e32 v12, 16, v7
	v_and_b32_e32 v7, 0xffff0000, v7
	v_lshlrev_b32_e32 v13, 16, v8
	v_and_b32_e32 v8, 0xffff0000, v8
	v_lshlrev_b32_e32 v14, 16, v9
	v_and_b32_e32 v9, 0xffff0000, v9
	v_mul_f32_e32 v0, v168, v0
	v_sub_f32_e32 v6, v6, v10
	v_sub_f32_e32 v12, v12, v10
	v_sub_f32_e32 v7, v7, v10
	v_sub_f32_e32 v13, v13, v10
	v_sub_f32_e32 v8, v8, v10
	v_sub_f32_e32 v14, v14, v10
	v_sub_f32_e32 v9, v9, v10
	v_mul_f32_e32 v6, v11, v6
	v_mul_f32_e32 v12, v11, v12
	v_mul_f32_e32 v7, v11, v7
	v_mul_f32_e32 v13, v11, v13
	v_mul_f32_e32 v8, v11, v8
	v_mul_f32_e32 v14, v11, v14
	v_mul_f32_e32 v9, v11, v9
	v_xor_b32_e32 v10, v70, v73
	v_lshlrev_b32_e32 v10, 1, v10
	v_bfe_u32 v11, v0, 16, 1
	v_mul_f32_e32 v6, v169, v6
	v_add3_u32 v0, v0, v11, s90
	v_add3_u32 v10, 0, v10, v32
	ds_write_b16_d16_hi v10, v0 offset:34816
	v_bfe_u32 v0, v6, 16, 1
	v_mul_f32_e32 v12, v170, v12
	v_add3_u32 v0, v6, v0, s90
	ds_write_b16_d16_hi v10, v0 offset:35088
	v_bfe_u32 v0, v12, 16, 1
	v_mul_f32_e32 v7, v171, v7
	v_add3_u32 v0, v12, v0, s90
	ds_write_b16_d16_hi v10, v0 offset:35360
	v_bfe_u32 v0, v7, 16, 1
	v_mul_f32_e32 v13, v172, v13
	v_add3_u32 v0, v7, v0, s90
	ds_write_b16_d16_hi v10, v0 offset:35632
	v_bfe_u32 v0, v13, 16, 1
	v_mul_f32_e32 v8, v173, v8
	v_add3_u32 v0, v13, v0, s90
	ds_write_b16_d16_hi v10, v0 offset:35904
	v_bfe_u32 v0, v8, 16, 1
	v_mul_f32_e32 v14, v174, v14
	v_add3_u32 v0, v8, v0, s90
	ds_write_b16_d16_hi v10, v0 offset:36176
	v_bfe_u32 v0, v14, 16, 1
	v_add3_u32 v0, v14, v0, s90
	ds_write_b16_d16_hi v10, v0 offset:36448
	v_lshl_add_u32 v0, v69, 2, s12
	ds_read2st64_b32 v[6:7], v0 offset1:2
	v_mul_f32_e32 v9, v175, v9
	v_bfe_u32 v0, v9, 16, 1
	v_add3_u32 v0, v9, v0, s90
	ds_write_b16_d16_hi v10, v0 offset:36720
	v_lshlrev_b32_e32 v0, 16, v2
	s_waitcnt lgkmcnt(1)
	v_sub_f32_e32 v0, v0, v6
	v_mul_f32_e32 v0, v7, v0
	v_and_b32_e32 v2, 0xffff0000, v2
	v_lshlrev_b32_e32 v8, 16, v3
	v_and_b32_e32 v3, 0xffff0000, v3
	v_lshlrev_b32_e32 v9, 16, v4
	v_and_b32_e32 v4, 0xffff0000, v4
	v_lshlrev_b32_e32 v10, 16, v5
	v_and_b32_e32 v5, 0xffff0000, v5
	v_mul_f32_e32 v0, v168, v0
	v_sub_f32_e32 v2, v2, v6
	v_sub_f32_e32 v8, v8, v6
	v_sub_f32_e32 v3, v3, v6
	v_sub_f32_e32 v9, v9, v6
	v_sub_f32_e32 v4, v4, v6
	v_sub_f32_e32 v10, v10, v6
	v_sub_f32_e32 v5, v5, v6
	v_mul_f32_e32 v2, v7, v2
	v_mul_f32_e32 v8, v7, v8
	v_mul_f32_e32 v3, v7, v3
	v_mul_f32_e32 v9, v7, v9
	v_mul_f32_e32 v4, v7, v4
	v_mul_f32_e32 v10, v7, v10
	v_mul_f32_e32 v5, v7, v5
	v_xor_b32_e32 v6, v69, v73
	v_lshlrev_b32_e32 v6, 1, v6
	v_bfe_u32 v7, v0, 16, 1
	v_mul_f32_e32 v2, v169, v2
	v_add3_u32 v0, v0, v7, s90
	v_add3_u32 v6, 0, v6, v32
	ds_write_b16_d16_hi v6, v0 offset:34816
	v_bfe_u32 v0, v2, 16, 1
	v_mul_f32_e32 v8, v170, v8
	v_add3_u32 v0, v2, v0, s90
	ds_write_b16_d16_hi v6, v0 offset:35088
	v_bfe_u32 v0, v8, 16, 1
	v_mul_f32_e32 v3, v171, v3
	v_add3_u32 v0, v8, v0, s90
	ds_write_b16_d16_hi v6, v0 offset:35360
	v_bfe_u32 v0, v3, 16, 1
	v_mul_f32_e32 v9, v172, v9
	v_add3_u32 v0, v3, v0, s90
	ds_write_b16_d16_hi v6, v0 offset:35632
	v_bfe_u32 v0, v9, 16, 1
	v_mul_f32_e32 v4, v173, v4
	v_add3_u32 v0, v9, v0, s90
	ds_write_b16_d16_hi v6, v0 offset:35904
	v_bfe_u32 v0, v4, 16, 1
	v_mul_f32_e32 v10, v174, v10
	v_add3_u32 v0, v4, v0, s90
	ds_write_b16_d16_hi v6, v0 offset:36176
	v_bfe_u32 v0, v10, 16, 1
	v_mul_f32_e32 v5, v175, v5
	v_add3_u32 v0, v10, v0, s90
	ds_write_b16_d16_hi v6, v0 offset:36448
	v_bfe_u32 v0, v5, 16, 1
	v_add3_u32 v0, v5, v0, s90
	ds_write_b16_d16_hi v6, v0 offset:36720
	v_bfe_u32 v18, v68, 4, 2
	v_bfi_b32 v0, -16, v72, v68
	v_and_b32_e32 v200, 0x18, v0
	v_lshrrev_b32_e32 v201, 5, v0
	v_lshlrev_b32_e32 v200, 1, v200
	v_and_b32_e32 v201, 3, v201
	v_and_b32_e32 v19, -16, v72
	v_mul_lo_u32 v0, v0, s14
	v_lshlrev_b32_e32 v22, 4, v18
	v_lshlrev_b32_e32 v201, 6, v201
	v_xor_b32_e32 v200, v22, v200
	v_add3_u32 v0, 0, v0, v200
	v_xor_b32_e32 v203, 64, v201
	v_xor_b32_e32 v204, 0x80, v201
	v_xor_b32_e32 v205, 0xc0, v201
	v_add_u32_e32 v202, v0, v201
	v_add_u32_e32 v203, v0, v203
	v_add_u32_e32 v204, v0, v204
	v_add_u32_e32 v205, v0, v205
	v_lshl_or_b32 v18, v18, 2, v19
	s_waitcnt lgkmcnt(0)
	s_barrier
	v_and_b32_e32 v23, 15, v68
	ds_read_b128 v[2:5], v202 offset:34816
	ds_read_b128 v[6:9], v203 offset:34816
	ds_read_b128 v[10:13], v204 offset:34816
	ds_read_b128 v[14:17], v205 offset:34816
	v_mov_b32_e32 v0, s20
	v_ashrrev_i32_e32 v19, 31, v18
	v_lshl_add_u64 v[24:25], v[18:19], 1, v[0:1]
	v_add_lshl_u32 v0, s11, v23, 11
	s_ashr_i32 s12, s6, 31
	v_or_b32_e32 v20, s6, v23
	v_lshl_add_u64 v[18:19], v[24:25], 0, v[0:1]
	v_mul_u32_u24_e32 v0, 0x110, v23
	s_add_i32 s6, s16, s7
	v_add3_u32 v26, v0, v22, 0
	v_add_u32_e32 v22, s6, v23
	s_lshl_b32 s6, s10, 16
	s_and_b32 s6, s6, 0x3fc0000
	v_mov_b32_e32 v21, s12
	v_lshl_or_b32 v0, v23, 11, s6
	v_lshl_add_u64 v[20:21], v[20:21], 2, s[8:9]
	v_lshl_add_u64 v[24:25], v[24:25], 0, v[0:1]
	v_lshl_add_u64 v[18:19], s[64:65], 0, v[18:19]
	v_lshl_add_u64 v[20:21], v[20:21], 0, 64
	v_lshl_add_u64 v[24:25], s[64:65], 0, v[24:25]
	s_mov_b64 s[6:7], 0
